# XQ projection epilogue: Q tiles stored with the default cache policy (not nt) since the same workgroup reads them back in its cross-attention units; MIXPROJ keeps nt
# speedup vs baseline: 1.0032x; 1.0007x over previous
; __device__ __forceinline__ unsigned cvt_pk_bf16(float lo, float hi) { unsigned r; asm volatile("v_cvt_pk_bf16_f32 %0, %1, %2" : "=v"(r) : "v"(lo), "v"(hi)); return r; }
;     __device__ __forceinline__ void operator()(const f32x4 (&acc)[2][2][4][2], const Unit& u, int wr, int wc, int fr, int fq) const {
;     ...
;         for (int ai = 0; ai < 2; ++ai)
; #pragma unroll
;             for (int m = 0; m < 4; ++m) { const int row = row0 + ai * HALF + m * 16; bf16_t* rowp = O + (size_t)row * ldc + col0;
;                 float sc = 1.f; if (SCALE) sc = rsl ? rsl[((u.pm - pm0) >> 3) * 256 + (row & 255)] : row_rstd(ssq, row);
; #pragma unroll
;                 for (int bj = 0; bj < 2; ++bj) { f32x4 v0 = acc[ai][bj][m][0] * sc, v1 = acc[ai][bj][m][1] * sc;
;                     if (ACT == 1) {
; #pragma unroll
;                         for (int j = 0; j < 4; ++j) { const float a = __builtin_fmaxf(v0[j], 0.f), b = __builtin_fmaxf(v1[j], 0.f); v0[j] = a * a; v1[j] = b * b; } }
;                     u32x4 w; w.x = cvt_pk_bf16(v0[0], v0[1]); w.y = cvt_pk_bf16(v0[2], v0[3]); w.z = cvt_pk_bf16(v1[0], v1[1]); w.w = cvt_pk_bf16(v1[2], v1[3]);
;                     __builtin_nontemporal_store(w, (u32x4*)(rowp + bj * HALF)); } }
.LBB0_512:
	s_and_b64 vcc, exec, s[76:77]
	s_cbranch_vccz .LBB0_580
	v_ashrrev_i32_e32 v143, 31, v142
	s_and_b64 vcc, exec, s[60:61]
	s_cbranch_vccnz .Lmpe_slow
	v_readlane_b32 vcc_lo, v255, 15
	s_cmp_eq_u32 vcc_lo, 6
	s_cbranch_scc1 .Lmpe_xq
	s_sub_i32 s67, s6, s20
	s_lshl_b32 s67, s67, 7
	s_and_b32 s67, s67, 0xfffffc00
	v_add_u32_e32 v0, s67, v150
	ds_read_b32 v226, v0 offset:0
	ds_read_b32 v228, v0 offset:64
	ds_read_b32 v230, v0 offset:128
	ds_read_b32 v232, v0 offset:192
	ds_read_b32 v234, v0 offset:512
	ds_read_b32 v236, v0 offset:576
	ds_read_b32 v238, v0 offset:640
	ds_read_b32 v240, v0 offset:704
	v_lshl_or_b32 v144, s74, 8, v151
	v_ashrrev_i32_e32 v145, 31, v144
	v_mul_lo_u32 v154, v142, s54
	v_mov_b32_e32 v155, 0
	v_lshl_add_u64 v[154:155], v[154:155], 1, s[52:53]
	v_lshl_add_u64 v[154:155], v[144:145], 1, v[154:155]
	s_lshl_b32 s74, s54, 5
	s_lshl_b32 s75, s54, 8
	s_waitcnt lgkmcnt(7)
	v_mov_b32_e32 v156, v154
	v_mov_b32_e32 v157, v155
	v_pk_mul_f32 v[114:115], v[114:115], v[226:227] op_sel_hi:[1,0]
	v_pk_mul_f32 v[116:117], v[116:117], v[226:227] op_sel_hi:[1,0]
	v_pk_mul_f32 v[118:119], v[118:119], v[226:227] op_sel_hi:[1,0]
	v_pk_mul_f32 v[120:121], v[120:121], v[226:227] op_sel_hi:[1,0]
	v_pk_mul_f32 v[122:123], v[122:123], v[226:227] op_sel_hi:[1,0]
	v_pk_mul_f32 v[124:125], v[124:125], v[226:227] op_sel_hi:[1,0]
	v_pk_mul_f32 v[126:127], v[126:127], v[226:227] op_sel_hi:[1,0]
	v_pk_mul_f32 v[128:129], v[128:129], v[226:227] op_sel_hi:[1,0]
	v_cvt_pk_bf16_f32 v158, v126, v127
	v_cvt_pk_bf16_f32 v159, v128, v129
	v_cvt_pk_bf16_f32 v160, v122, v123
	v_cvt_pk_bf16_f32 v161, v124, v125
	global_store_dwordx4 v[156:157], v[158:161], off nt
	v_cvt_pk_bf16_f32 v162, v118, v119
	v_cvt_pk_bf16_f32 v163, v120, v121
	v_cvt_pk_bf16_f32 v164, v114, v115
	v_cvt_pk_bf16_f32 v165, v116, v117
	global_store_dwordx4 v[156:157], v[162:165], off offset:256 nt
	s_waitcnt lgkmcnt(6)
	v_add_co_u32_e32 v156, vcc, s74, v156
	v_addc_co_u32_e32 v157, vcc, 0, v157, vcc
	v_pk_mul_f32 v[98:99], v[98:99], v[228:229] op_sel_hi:[1,0]
	v_pk_mul_f32 v[100:101], v[100:101], v[228:229] op_sel_hi:[1,0]
	v_pk_mul_f32 v[102:103], v[102:103], v[228:229] op_sel_hi:[1,0]
	v_pk_mul_f32 v[104:105], v[104:105], v[228:229] op_sel_hi:[1,0]
	v_pk_mul_f32 v[106:107], v[106:107], v[228:229] op_sel_hi:[1,0]
	v_pk_mul_f32 v[108:109], v[108:109], v[228:229] op_sel_hi:[1,0]
	v_pk_mul_f32 v[110:111], v[110:111], v[228:229] op_sel_hi:[1,0]
	v_pk_mul_f32 v[112:113], v[112:113], v[228:229] op_sel_hi:[1,0]
	v_cvt_pk_bf16_f32 v166, v110, v111
	v_cvt_pk_bf16_f32 v167, v112, v113
	v_cvt_pk_bf16_f32 v168, v106, v107
	v_cvt_pk_bf16_f32 v169, v108, v109
	global_store_dwordx4 v[156:157], v[166:169], off nt
	v_cvt_pk_bf16_f32 v170, v102, v103
	v_cvt_pk_bf16_f32 v171, v104, v105
	v_cvt_pk_bf16_f32 v172, v98, v99
	v_cvt_pk_bf16_f32 v173, v100, v101
	global_store_dwordx4 v[156:157], v[170:173], off offset:256 nt
	s_waitcnt lgkmcnt(5)
	v_add_co_u32_e32 v156, vcc, s74, v156
	v_addc_co_u32_e32 v157, vcc, 0, v157, vcc
	v_pk_mul_f32 v[82:83], v[82:83], v[230:231] op_sel_hi:[1,0]
	v_pk_mul_f32 v[84:85], v[84:85], v[230:231] op_sel_hi:[1,0]
	v_pk_mul_f32 v[86:87], v[86:87], v[230:231] op_sel_hi:[1,0]
	v_pk_mul_f32 v[88:89], v[88:89], v[230:231] op_sel_hi:[1,0]
	v_pk_mul_f32 v[90:91], v[90:91], v[230:231] op_sel_hi:[1,0]
	v_pk_mul_f32 v[92:93], v[92:93], v[230:231] op_sel_hi:[1,0]
	v_pk_mul_f32 v[94:95], v[94:95], v[230:231] op_sel_hi:[1,0]
	v_pk_mul_f32 v[96:97], v[96:97], v[230:231] op_sel_hi:[1,0]
	v_cvt_pk_bf16_f32 v158, v94, v95
	v_cvt_pk_bf16_f32 v159, v96, v97
	v_cvt_pk_bf16_f32 v160, v90, v91
	v_cvt_pk_bf16_f32 v161, v92, v93
	global_store_dwordx4 v[156:157], v[158:161], off nt
	v_cvt_pk_bf16_f32 v162, v86, v87
	v_cvt_pk_bf16_f32 v163, v88, v89
	v_cvt_pk_bf16_f32 v164, v82, v83
	v_cvt_pk_bf16_f32 v165, v84, v85
	global_store_dwordx4 v[156:157], v[162:165], off offset:256 nt
	s_waitcnt lgkmcnt(4)
	v_add_co_u32_e32 v156, vcc, s74, v156
	v_addc_co_u32_e32 v157, vcc, 0, v157, vcc
	v_pk_mul_f32 v[66:67], v[66:67], v[232:233] op_sel_hi:[1,0]
	v_pk_mul_f32 v[68:69], v[68:69], v[232:233] op_sel_hi:[1,0]
	v_pk_mul_f32 v[70:71], v[70:71], v[232:233] op_sel_hi:[1,0]
	v_pk_mul_f32 v[72:73], v[72:73], v[232:233] op_sel_hi:[1,0]
	v_pk_mul_f32 v[74:75], v[74:75], v[232:233] op_sel_hi:[1,0]
	v_pk_mul_f32 v[76:77], v[76:77], v[232:233] op_sel_hi:[1,0]
	v_pk_mul_f32 v[78:79], v[78:79], v[232:233] op_sel_hi:[1,0]
	v_pk_mul_f32 v[80:81], v[80:81], v[232:233] op_sel_hi:[1,0]
	v_cvt_pk_bf16_f32 v166, v78, v79
	v_cvt_pk_bf16_f32 v167, v80, v81
	v_cvt_pk_bf16_f32 v168, v74, v75
	v_cvt_pk_bf16_f32 v169, v76, v77
	global_store_dwordx4 v[156:157], v[166:169], off nt
	v_cvt_pk_bf16_f32 v170, v70, v71
	v_cvt_pk_bf16_f32 v171, v72, v73
	v_cvt_pk_bf16_f32 v172, v66, v67
	v_cvt_pk_bf16_f32 v173, v68, v69
	global_store_dwordx4 v[156:157], v[170:173], off offset:256 nt
	s_waitcnt lgkmcnt(3)
	v_add_co_u32_e32 v156, vcc, s75, v154
	v_addc_co_u32_e32 v157, vcc, 0, v155, vcc
	v_pk_mul_f32 v[50:51], v[50:51], v[234:235] op_sel_hi:[1,0]
	v_pk_mul_f32 v[52:53], v[52:53], v[234:235] op_sel_hi:[1,0]
	v_pk_mul_f32 v[54:55], v[54:55], v[234:235] op_sel_hi:[1,0]
	v_pk_mul_f32 v[56:57], v[56:57], v[234:235] op_sel_hi:[1,0]
	v_pk_mul_f32 v[58:59], v[58:59], v[234:235] op_sel_hi:[1,0]
	v_pk_mul_f32 v[60:61], v[60:61], v[234:235] op_sel_hi:[1,0]
	v_pk_mul_f32 v[62:63], v[62:63], v[234:235] op_sel_hi:[1,0]
	v_pk_mul_f32 v[64:65], v[64:65], v[234:235] op_sel_hi:[1,0]
	v_cvt_pk_bf16_f32 v158, v62, v63
	v_cvt_pk_bf16_f32 v159, v64, v65
	v_cvt_pk_bf16_f32 v160, v58, v59
	v_cvt_pk_bf16_f32 v161, v60, v61
	global_store_dwordx4 v[156:157], v[158:161], off nt
	v_cvt_pk_bf16_f32 v162, v54, v55
	v_cvt_pk_bf16_f32 v163, v56, v57
	v_cvt_pk_bf16_f32 v164, v50, v51
	v_cvt_pk_bf16_f32 v165, v52, v53
	global_store_dwordx4 v[156:157], v[162:165], off offset:256 nt
	s_waitcnt lgkmcnt(2)
; __device__ __forceinline__ unsigned cvt_pk_bf16(float lo, float hi) { unsigned r; asm volatile("v_cvt_pk_bf16_f32 %0, %1, %2" : "=v"(r) : "v"(lo), "v"(hi)); return r; }
;     __device__ __forceinline__ void operator()(const f32x4 (&acc)[2][2][4][2], const Unit& u, int wr, int wc, int fr, int fq) const {
;     ...
;         for (int ai = 0; ai < 2; ++ai)
; #pragma unroll
;             for (int m = 0; m < 4; ++m) { const int row = row0 + ai * HALF + m * 16; bf16_t* rowp = O + (size_t)row * ldc + col0;
;                 float sc = 1.f; if (SCALE) sc = rsl ? rsl[((u.pm - pm0) >> 3) * 256 + (row & 255)] : row_rstd(ssq, row);
; #pragma unroll
;                 for (int bj = 0; bj < 2; ++bj) { f32x4 v0 = acc[ai][bj][m][0] * sc, v1 = acc[ai][bj][m][1] * sc;
;                     if (ACT == 1) {
; #pragma unroll
;                         for (int j = 0; j < 4; ++j) { const float a = __builtin_fmaxf(v0[j], 0.f), b = __builtin_fmaxf(v1[j], 0.f); v0[j] = a * a; v1[j] = b * b; } }
;                     u32x4 w; w.x = cvt_pk_bf16(v0[0], v0[1]); w.y = cvt_pk_bf16(v0[2], v0[3]); w.z = cvt_pk_bf16(v1[0], v1[1]); w.w = cvt_pk_bf16(v1[2], v1[3]);
;                     __builtin_nontemporal_store(w, (u32x4*)(rowp + bj * HALF)); } }
	v_add_co_u32_e32 v156, vcc, s74, v156
	v_addc_co_u32_e32 v157, vcc, 0, v157, vcc
	v_pk_mul_f32 v[34:35], v[34:35], v[236:237] op_sel_hi:[1,0]
	v_pk_mul_f32 v[36:37], v[36:37], v[236:237] op_sel_hi:[1,0]
	v_pk_mul_f32 v[38:39], v[38:39], v[236:237] op_sel_hi:[1,0]
	v_pk_mul_f32 v[40:41], v[40:41], v[236:237] op_sel_hi:[1,0]
	v_pk_mul_f32 v[42:43], v[42:43], v[236:237] op_sel_hi:[1,0]
	v_pk_mul_f32 v[44:45], v[44:45], v[236:237] op_sel_hi:[1,0]
	v_pk_mul_f32 v[46:47], v[46:47], v[236:237] op_sel_hi:[1,0]
	v_pk_mul_f32 v[48:49], v[48:49], v[236:237] op_sel_hi:[1,0]
	v_cvt_pk_bf16_f32 v166, v46, v47
	v_cvt_pk_bf16_f32 v167, v48, v49
	v_cvt_pk_bf16_f32 v168, v42, v43
	v_cvt_pk_bf16_f32 v169, v44, v45
	global_store_dwordx4 v[156:157], v[166:169], off nt
	v_cvt_pk_bf16_f32 v170, v38, v39
	v_cvt_pk_bf16_f32 v171, v40, v41
	v_cvt_pk_bf16_f32 v172, v34, v35
	v_cvt_pk_bf16_f32 v173, v36, v37
	global_store_dwordx4 v[156:157], v[170:173], off offset:256 nt
	s_waitcnt lgkmcnt(1)
	v_add_co_u32_e32 v156, vcc, s74, v156
	v_addc_co_u32_e32 v157, vcc, 0, v157, vcc
	v_pk_mul_f32 v[18:19], v[18:19], v[238:239] op_sel_hi:[1,0]
	v_pk_mul_f32 v[20:21], v[20:21], v[238:239] op_sel_hi:[1,0]
	v_pk_mul_f32 v[22:23], v[22:23], v[238:239] op_sel_hi:[1,0]
	v_pk_mul_f32 v[24:25], v[24:25], v[238:239] op_sel_hi:[1,0]
	v_pk_mul_f32 v[26:27], v[26:27], v[238:239] op_sel_hi:[1,0]
	v_pk_mul_f32 v[28:29], v[28:29], v[238:239] op_sel_hi:[1,0]
	v_pk_mul_f32 v[30:31], v[30:31], v[238:239] op_sel_hi:[1,0]
	v_pk_mul_f32 v[32:33], v[32:33], v[238:239] op_sel_hi:[1,0]
	v_cvt_pk_bf16_f32 v158, v30, v31
	v_cvt_pk_bf16_f32 v159, v32, v33
	v_cvt_pk_bf16_f32 v160, v26, v27
	v_cvt_pk_bf16_f32 v161, v28, v29
	global_store_dwordx4 v[156:157], v[158:161], off nt
	v_cvt_pk_bf16_f32 v162, v22, v23
	v_cvt_pk_bf16_f32 v163, v24, v25
	v_cvt_pk_bf16_f32 v164, v18, v19
	v_cvt_pk_bf16_f32 v165, v20, v21
	global_store_dwordx4 v[156:157], v[162:165], off offset:256 nt
	s_waitcnt lgkmcnt(0)
	v_add_co_u32_e32 v156, vcc, s74, v156
	v_addc_co_u32_e32 v157, vcc, 0, v157, vcc
	v_pk_mul_f32 v[2:3], v[2:3], v[240:241] op_sel_hi:[1,0]
	v_pk_mul_f32 v[4:5], v[4:5], v[240:241] op_sel_hi:[1,0]
	v_pk_mul_f32 v[6:7], v[6:7], v[240:241] op_sel_hi:[1,0]
	v_pk_mul_f32 v[8:9], v[8:9], v[240:241] op_sel_hi:[1,0]
	v_pk_mul_f32 v[10:11], v[10:11], v[240:241] op_sel_hi:[1,0]
	v_pk_mul_f32 v[12:13], v[12:13], v[240:241] op_sel_hi:[1,0]
	v_pk_mul_f32 v[14:15], v[14:15], v[240:241] op_sel_hi:[1,0]
	v_pk_mul_f32 v[16:17], v[16:17], v[240:241] op_sel_hi:[1,0]
	v_cvt_pk_bf16_f32 v166, v14, v15
	v_cvt_pk_bf16_f32 v167, v16, v17
	v_cvt_pk_bf16_f32 v168, v10, v11
	v_cvt_pk_bf16_f32 v169, v12, v13
	global_store_dwordx4 v[156:157], v[166:169], off nt
	v_cvt_pk_bf16_f32 v170, v6, v7
	v_cvt_pk_bf16_f32 v171, v8, v9
	v_cvt_pk_bf16_f32 v172, v2, v3
	v_cvt_pk_bf16_f32 v173, v4, v5
	global_store_dwordx4 v[156:157], v[170:173], off offset:256 nt
	s_branch .LBB0_580
.Lmpe_xq:
	s_sub_i32 s67, s6, s20
	s_lshl_b32 s67, s67, 7
	s_and_b32 s67, s67, 0xfffffc00
	v_add_u32_e32 v0, s67, v150
	ds_read_b32 v226, v0 offset:0
	ds_read_b32 v228, v0 offset:64
	ds_read_b32 v230, v0 offset:128
	ds_read_b32 v232, v0 offset:192
	ds_read_b32 v234, v0 offset:512
	ds_read_b32 v236, v0 offset:576
	ds_read_b32 v238, v0 offset:640
	ds_read_b32 v240, v0 offset:704
	v_lshl_or_b32 v144, s74, 8, v151
	v_ashrrev_i32_e32 v145, 31, v144
	v_mul_lo_u32 v154, v142, s54
	v_mov_b32_e32 v155, 0
	v_lshl_add_u64 v[154:155], v[154:155], 1, s[52:53]
	v_lshl_add_u64 v[154:155], v[144:145], 1, v[154:155]
	s_lshl_b32 s74, s54, 5
	s_lshl_b32 s75, s54, 8
	s_waitcnt lgkmcnt(7)
	v_mov_b32_e32 v156, v154
	v_mov_b32_e32 v157, v155
	v_pk_mul_f32 v[114:115], v[114:115], v[226:227] op_sel_hi:[1,0]
	v_pk_mul_f32 v[116:117], v[116:117], v[226:227] op_sel_hi:[1,0]
	v_pk_mul_f32 v[118:119], v[118:119], v[226:227] op_sel_hi:[1,0]
	v_pk_mul_f32 v[120:121], v[120:121], v[226:227] op_sel_hi:[1,0]
	v_pk_mul_f32 v[122:123], v[122:123], v[226:227] op_sel_hi:[1,0]
	v_pk_mul_f32 v[124:125], v[124:125], v[226:227] op_sel_hi:[1,0]
	v_pk_mul_f32 v[126:127], v[126:127], v[226:227] op_sel_hi:[1,0]
	v_pk_mul_f32 v[128:129], v[128:129], v[226:227] op_sel_hi:[1,0]
	v_cvt_pk_bf16_f32 v158, v126, v127
	v_cvt_pk_bf16_f32 v159, v128, v129
	v_cvt_pk_bf16_f32 v160, v122, v123
	v_cvt_pk_bf16_f32 v161, v124, v125
	global_store_dwordx4 v[156:157], v[158:161], off
	v_cvt_pk_bf16_f32 v162, v118, v119
	v_cvt_pk_bf16_f32 v163, v120, v121
	v_cvt_pk_bf16_f32 v164, v114, v115
	v_cvt_pk_bf16_f32 v165, v116, v117
	global_store_dwordx4 v[156:157], v[162:165], off offset:256
	s_waitcnt lgkmcnt(6)
	v_add_co_u32_e32 v156, vcc, s74, v156
	v_addc_co_u32_e32 v157, vcc, 0, v157, vcc
	v_pk_mul_f32 v[98:99], v[98:99], v[228:229] op_sel_hi:[1,0]
	v_pk_mul_f32 v[100:101], v[100:101], v[228:229] op_sel_hi:[1,0]
	v_pk_mul_f32 v[102:103], v[102:103], v[228:229] op_sel_hi:[1,0]
	v_pk_mul_f32 v[104:105], v[104:105], v[228:229] op_sel_hi:[1,0]
	v_pk_mul_f32 v[106:107], v[106:107], v[228:229] op_sel_hi:[1,0]
	v_pk_mul_f32 v[108:109], v[108:109], v[228:229] op_sel_hi:[1,0]
	v_pk_mul_f32 v[110:111], v[110:111], v[228:229] op_sel_hi:[1,0]
	v_pk_mul_f32 v[112:113], v[112:113], v[228:229] op_sel_hi:[1,0]
	v_cvt_pk_bf16_f32 v166, v110, v111
	v_cvt_pk_bf16_f32 v167, v112, v113
	v_cvt_pk_bf16_f32 v168, v106, v107
	v_cvt_pk_bf16_f32 v169, v108, v109
	global_store_dwordx4 v[156:157], v[166:169], off
	v_cvt_pk_bf16_f32 v170, v102, v103
	v_cvt_pk_bf16_f32 v171, v104, v105
	v_cvt_pk_bf16_f32 v172, v98, v99
	v_cvt_pk_bf16_f32 v173, v100, v101
	global_store_dwordx4 v[156:157], v[170:173], off offset:256
	s_waitcnt lgkmcnt(5)
; __device__ __forceinline__ unsigned cvt_pk_bf16(float lo, float hi) { unsigned r; asm volatile("v_cvt_pk_bf16_f32 %0, %1, %2" : "=v"(r) : "v"(lo), "v"(hi)); return r; }
;     __device__ __forceinline__ void operator()(const f32x4 (&acc)[2][2][4][2], const Unit& u, int wr, int wc, int fr, int fq) const {
;     ...
;         for (int ai = 0; ai < 2; ++ai)
; #pragma unroll
;             for (int m = 0; m < 4; ++m) { const int row = row0 + ai * HALF + m * 16; bf16_t* rowp = O + (size_t)row * ldc + col0;
;                 float sc = 1.f; if (SCALE) sc = rsl ? rsl[((u.pm - pm0) >> 3) * 256 + (row & 255)] : row_rstd(ssq, row);
; #pragma unroll
;                 for (int bj = 0; bj < 2; ++bj) { f32x4 v0 = acc[ai][bj][m][0] * sc, v1 = acc[ai][bj][m][1] * sc;
;                     if (ACT == 1) {
; #pragma unroll
;                         for (int j = 0; j < 4; ++j) { const float a = __builtin_fmaxf(v0[j], 0.f), b = __builtin_fmaxf(v1[j], 0.f); v0[j] = a * a; v1[j] = b * b; } }
;                     u32x4 w; w.x = cvt_pk_bf16(v0[0], v0[1]); w.y = cvt_pk_bf16(v0[2], v0[3]); w.z = cvt_pk_bf16(v1[0], v1[1]); w.w = cvt_pk_bf16(v1[2], v1[3]);
;                     __builtin_nontemporal_store(w, (u32x4*)(rowp + bj * HALF)); } }
	v_add_co_u32_e32 v156, vcc, s74, v156
	v_addc_co_u32_e32 v157, vcc, 0, v157, vcc
	v_pk_mul_f32 v[82:83], v[82:83], v[230:231] op_sel_hi:[1,0]
	v_pk_mul_f32 v[84:85], v[84:85], v[230:231] op_sel_hi:[1,0]
	v_pk_mul_f32 v[86:87], v[86:87], v[230:231] op_sel_hi:[1,0]
	v_pk_mul_f32 v[88:89], v[88:89], v[230:231] op_sel_hi:[1,0]
	v_pk_mul_f32 v[90:91], v[90:91], v[230:231] op_sel_hi:[1,0]
	v_pk_mul_f32 v[92:93], v[92:93], v[230:231] op_sel_hi:[1,0]
	v_pk_mul_f32 v[94:95], v[94:95], v[230:231] op_sel_hi:[1,0]
	v_pk_mul_f32 v[96:97], v[96:97], v[230:231] op_sel_hi:[1,0]
	v_cvt_pk_bf16_f32 v158, v94, v95
	v_cvt_pk_bf16_f32 v159, v96, v97
	v_cvt_pk_bf16_f32 v160, v90, v91
	v_cvt_pk_bf16_f32 v161, v92, v93
	global_store_dwordx4 v[156:157], v[158:161], off
	v_cvt_pk_bf16_f32 v162, v86, v87
	v_cvt_pk_bf16_f32 v163, v88, v89
	v_cvt_pk_bf16_f32 v164, v82, v83
	v_cvt_pk_bf16_f32 v165, v84, v85
	global_store_dwordx4 v[156:157], v[162:165], off offset:256
	s_waitcnt lgkmcnt(4)
	v_add_co_u32_e32 v156, vcc, s74, v156
	v_addc_co_u32_e32 v157, vcc, 0, v157, vcc
	v_pk_mul_f32 v[66:67], v[66:67], v[232:233] op_sel_hi:[1,0]
	v_pk_mul_f32 v[68:69], v[68:69], v[232:233] op_sel_hi:[1,0]
	v_pk_mul_f32 v[70:71], v[70:71], v[232:233] op_sel_hi:[1,0]
	v_pk_mul_f32 v[72:73], v[72:73], v[232:233] op_sel_hi:[1,0]
	v_pk_mul_f32 v[74:75], v[74:75], v[232:233] op_sel_hi:[1,0]
	v_pk_mul_f32 v[76:77], v[76:77], v[232:233] op_sel_hi:[1,0]
	v_pk_mul_f32 v[78:79], v[78:79], v[232:233] op_sel_hi:[1,0]
	v_pk_mul_f32 v[80:81], v[80:81], v[232:233] op_sel_hi:[1,0]
	v_cvt_pk_bf16_f32 v166, v78, v79
	v_cvt_pk_bf16_f32 v167, v80, v81
	v_cvt_pk_bf16_f32 v168, v74, v75
	v_cvt_pk_bf16_f32 v169, v76, v77
	global_store_dwordx4 v[156:157], v[166:169], off
	v_cvt_pk_bf16_f32 v170, v70, v71
	v_cvt_pk_bf16_f32 v171, v72, v73
	v_cvt_pk_bf16_f32 v172, v66, v67
	v_cvt_pk_bf16_f32 v173, v68, v69
	global_store_dwordx4 v[156:157], v[170:173], off offset:256
	s_waitcnt lgkmcnt(3)
	v_add_co_u32_e32 v156, vcc, s75, v154
	v_addc_co_u32_e32 v157, vcc, 0, v155, vcc
	v_pk_mul_f32 v[50:51], v[50:51], v[234:235] op_sel_hi:[1,0]
	v_pk_mul_f32 v[52:53], v[52:53], v[234:235] op_sel_hi:[1,0]
	v_pk_mul_f32 v[54:55], v[54:55], v[234:235] op_sel_hi:[1,0]
	v_pk_mul_f32 v[56:57], v[56:57], v[234:235] op_sel_hi:[1,0]
	v_pk_mul_f32 v[58:59], v[58:59], v[234:235] op_sel_hi:[1,0]
	v_pk_mul_f32 v[60:61], v[60:61], v[234:235] op_sel_hi:[1,0]
	v_pk_mul_f32 v[62:63], v[62:63], v[234:235] op_sel_hi:[1,0]
	v_pk_mul_f32 v[64:65], v[64:65], v[234:235] op_sel_hi:[1,0]
	v_cvt_pk_bf16_f32 v158, v62, v63
	v_cvt_pk_bf16_f32 v159, v64, v65
	v_cvt_pk_bf16_f32 v160, v58, v59
	v_cvt_pk_bf16_f32 v161, v60, v61
	global_store_dwordx4 v[156:157], v[158:161], off
	v_cvt_pk_bf16_f32 v162, v54, v55
	v_cvt_pk_bf16_f32 v163, v56, v57
	v_cvt_pk_bf16_f32 v164, v50, v51
	v_cvt_pk_bf16_f32 v165, v52, v53
	global_store_dwordx4 v[156:157], v[162:165], off offset:256
	s_waitcnt lgkmcnt(2)
	v_add_co_u32_e32 v156, vcc, s74, v156
	v_addc_co_u32_e32 v157, vcc, 0, v157, vcc
	v_pk_mul_f32 v[34:35], v[34:35], v[236:237] op_sel_hi:[1,0]
	v_pk_mul_f32 v[36:37], v[36:37], v[236:237] op_sel_hi:[1,0]
	v_pk_mul_f32 v[38:39], v[38:39], v[236:237] op_sel_hi:[1,0]
	v_pk_mul_f32 v[40:41], v[40:41], v[236:237] op_sel_hi:[1,0]
	v_pk_mul_f32 v[42:43], v[42:43], v[236:237] op_sel_hi:[1,0]
	v_pk_mul_f32 v[44:45], v[44:45], v[236:237] op_sel_hi:[1,0]
	v_pk_mul_f32 v[46:47], v[46:47], v[236:237] op_sel_hi:[1,0]
	v_pk_mul_f32 v[48:49], v[48:49], v[236:237] op_sel_hi:[1,0]
	v_cvt_pk_bf16_f32 v166, v46, v47
	v_cvt_pk_bf16_f32 v167, v48, v49
	v_cvt_pk_bf16_f32 v168, v42, v43
	v_cvt_pk_bf16_f32 v169, v44, v45
	global_store_dwordx4 v[156:157], v[166:169], off
	v_cvt_pk_bf16_f32 v170, v38, v39
	v_cvt_pk_bf16_f32 v171, v40, v41
	v_cvt_pk_bf16_f32 v172, v34, v35
	v_cvt_pk_bf16_f32 v173, v36, v37
	global_store_dwordx4 v[156:157], v[170:173], off offset:256
	s_waitcnt lgkmcnt(1)
	v_add_co_u32_e32 v156, vcc, s74, v156
	v_addc_co_u32_e32 v157, vcc, 0, v157, vcc
	v_pk_mul_f32 v[18:19], v[18:19], v[238:239] op_sel_hi:[1,0]
	v_pk_mul_f32 v[20:21], v[20:21], v[238:239] op_sel_hi:[1,0]
	v_pk_mul_f32 v[22:23], v[22:23], v[238:239] op_sel_hi:[1,0]
	v_pk_mul_f32 v[24:25], v[24:25], v[238:239] op_sel_hi:[1,0]
	v_pk_mul_f32 v[26:27], v[26:27], v[238:239] op_sel_hi:[1,0]
	v_pk_mul_f32 v[28:29], v[28:29], v[238:239] op_sel_hi:[1,0]
	v_pk_mul_f32 v[30:31], v[30:31], v[238:239] op_sel_hi:[1,0]
	v_pk_mul_f32 v[32:33], v[32:33], v[238:239] op_sel_hi:[1,0]
	v_cvt_pk_bf16_f32 v158, v30, v31
	v_cvt_pk_bf16_f32 v159, v32, v33
	v_cvt_pk_bf16_f32 v160, v26, v27
	v_cvt_pk_bf16_f32 v161, v28, v29
	global_store_dwordx4 v[156:157], v[158:161], off
	v_cvt_pk_bf16_f32 v162, v22, v23
	v_cvt_pk_bf16_f32 v163, v24, v25
	v_cvt_pk_bf16_f32 v164, v18, v19
	v_cvt_pk_bf16_f32 v165, v20, v21
	global_store_dwordx4 v[156:157], v[162:165], off offset:256
	s_waitcnt lgkmcnt(0)
	v_add_co_u32_e32 v156, vcc, s74, v156
	v_addc_co_u32_e32 v157, vcc, 0, v157, vcc
	v_pk_mul_f32 v[2:3], v[2:3], v[240:241] op_sel_hi:[1,0]
	v_pk_mul_f32 v[4:5], v[4:5], v[240:241] op_sel_hi:[1,0]
	v_pk_mul_f32 v[6:7], v[6:7], v[240:241] op_sel_hi:[1,0]
	v_pk_mul_f32 v[8:9], v[8:9], v[240:241] op_sel_hi:[1,0]
	v_pk_mul_f32 v[10:11], v[10:11], v[240:241] op_sel_hi:[1,0]
	v_pk_mul_f32 v[12:13], v[12:13], v[240:241] op_sel_hi:[1,0]
	v_pk_mul_f32 v[14:15], v[14:15], v[240:241] op_sel_hi:[1,0]
	v_pk_mul_f32 v[16:17], v[16:17], v[240:241] op_sel_hi:[1,0]
	v_cvt_pk_bf16_f32 v166, v14, v15
	v_cvt_pk_bf16_f32 v167, v16, v17
	v_cvt_pk_bf16_f32 v168, v10, v11
	v_cvt_pk_bf16_f32 v169, v12, v13
	global_store_dwordx4 v[156:157], v[166:169], off
	v_cvt_pk_bf16_f32 v170, v6, v7
	v_cvt_pk_bf16_f32 v171, v8, v9
	v_cvt_pk_bf16_f32 v172, v2, v3
	v_cvt_pk_bf16_f32 v173, v4, v5
	global_store_dwordx4 v[156:157], v[170:173], off offset:256
	s_branch .LBB0_580
